# no grid barrier between prep and the k=3 GEMMs: prep outputs stored write-through, per-row-panel counters, each workgroup waits for the panels of its own tiles
# speedup vs baseline: 1.0088x; 1.0025x over previous
.LBB0_305:
	s_or_b64 exec, exec, s[2:3]
	s_waitcnt vmcnt(0)
	ds_write_b128 v69, v[0:3]
	v_add_u32_e32 v38, s7, v40
	v_mov_b64_e32 v[0:1], s[0:1]
	v_mad_i64_i32 v[24:25], s[2:3], v38, s22, v[0:1]
	v_lshl_add_u64 v[4:5], v[24:25], 0, v[64:65]
	global_load_dwordx4 v[26:29], v[4:5], off offset:1024
	global_load_dwordx4 v[86:89], v[4:5], off offset:1152
	global_load_dwordx4 v[90:93], v[4:5], off offset:1280
	global_load_dwordx4 v[16:19], v[4:5], off offset:1408
	global_load_dwordx4 v[8:11], v[4:5], off offset:1536
	global_load_dwordx4 v[0:3], v[4:5], off offset:1664
	global_load_dwordx4 v[94:97], v[4:5], off offset:1792
	global_load_dwordx4 v[20:23], v[4:5], off offset:1920
	global_load_dwordx4 v[12:15], v[4:5], off offset:2048
	s_nop 0
	global_load_dwordx4 v[4:7], v[4:5], off offset:2176
	v_ashrrev_i32_e32 v39, 31, v38
	s_waitcnt vmcnt(9)
	v_lshlrev_b32_e32 v31, 16, v27
	v_lshlrev_b32_e32 v30, 16, v26
	v_and_b32_e32 v27, 0xffff0000, v27
	v_and_b32_e32 v26, 0xffff0000, v26
	v_pk_mul_f32 v[26:27], v[26:27], v[26:27]
	s_waitcnt vmcnt(7)
	v_lshlrev_b32_e32 v99, 16, v91
	v_pk_fma_f32 v[26:27], v[30:31], v[30:31], v[26:27]
	v_lshlrev_b32_e32 v31, 16, v29
	v_lshlrev_b32_e32 v30, 16, v28
	v_and_b32_e32 v29, 0xffff0000, v29
	v_and_b32_e32 v28, 0xffff0000, v28
	v_pk_mul_f32 v[28:29], v[28:29], v[28:29]
	v_add_f32_e32 v26, v26, v27
	v_pk_fma_f32 v[28:29], v[30:31], v[30:31], v[28:29]
	v_lshlrev_b32_e32 v31, 16, v87
	v_lshlrev_b32_e32 v30, 16, v86
	v_and_b32_e32 v87, 0xffff0000, v87
	v_and_b32_e32 v86, 0xffff0000, v86
	v_pk_mul_f32 v[86:87], v[86:87], v[86:87]
	v_add_f32_e32 v26, v28, v26
	v_pk_fma_f32 v[30:31], v[30:31], v[30:31], v[86:87]
	v_lshlrev_b32_e32 v87, 16, v89
	v_lshlrev_b32_e32 v86, 16, v88
	v_and_b32_e32 v89, 0xffff0000, v89
	v_and_b32_e32 v88, 0xffff0000, v88
	v_add_f32_e32 v26, v29, v26
	v_pk_mul_f32 v[88:89], v[88:89], v[88:89]
	v_add_f32_e32 v26, v30, v26
	v_pk_fma_f32 v[86:87], v[86:87], v[86:87], v[88:89]
	v_add_f32_e32 v26, v31, v26
	v_add_f32_e32 v26, v86, v26
	v_pk_add_f32 v[28:29], v[86:87], v[26:27] op_sel_hi:[1,0]
	v_lshlrev_b32_e32 v26, 16, v90
	v_and_b32_e32 v27, 0xffff0000, v90
	v_mul_f32_e32 v28, v26, v26
	v_pk_fma_f32 v[30:31], v[26:27], v[26:27], v[28:29] op_sel_hi:[1,1,0]
	v_and_b32_e32 v91, 0xffff0000, v91
	s_waitcnt vmcnt(3)
	v_and_b32_e32 v90, 0xffff0000, v94
	v_lshlrev_b32_e32 v26, 16, v95
	v_and_b32_e32 v28, 0xffff0000, v95
	v_and_b32_e32 v89, 0xffff0000, v92
	v_lshlrev_b32_e32 v98, 16, v94
	v_mul_f32_e32 v30, v26, v26
	v_mul_f32_e32 v28, v28, v28
	v_and_b32_e32 v88, 0xffff0000, v96
	v_pk_mul_f32 v[90:91], v[90:91], v[90:91]
	v_lshlrev_b32_e32 v87, 16, v92
	v_lshlrev_b32_e32 v86, 16, v96
	v_pk_fma_f32 v[90:91], v[98:99], v[98:99], v[90:91]
	v_pk_add_f32 v[28:29], v[30:31], v[28:29]
	v_pk_mul_f32 v[30:31], v[88:89], v[88:89]
	v_pk_add_f32 v[28:29], v[90:91], v[28:29]
	v_pk_fma_f32 v[30:31], v[86:87], v[86:87], v[30:31]
	v_and_b32_e32 v87, 0xffff0000, v93
	v_and_b32_e32 v86, 0xffff0000, v97
	v_pk_add_f32 v[28:29], v[30:31], v[28:29]
	v_lshlrev_b32_e32 v31, 16, v93
	v_lshlrev_b32_e32 v30, 16, v97
	v_pk_mul_f32 v[86:87], v[86:87], v[86:87]
	s_waitcnt vmcnt(0)
	v_lshlrev_b32_e32 v26, 16, v5
	v_pk_fma_f32 v[30:31], v[30:31], v[30:31], v[86:87]
	v_and_b32_e32 v87, 0xffff0000, v16
	v_and_b32_e32 v86, 0xffff0000, v20
	v_pk_add_f32 v[28:29], v[30:31], v[28:29]
	v_lshlrev_b32_e32 v31, 16, v16
	v_lshlrev_b32_e32 v30, 16, v20
	v_pk_mul_f32 v[86:87], v[86:87], v[86:87]
	v_and_b32_e32 v16, 0xffff0000, v21
	v_pk_fma_f32 v[30:31], v[30:31], v[30:31], v[86:87]
	v_lshlrev_b32_e32 v20, 16, v22
	v_pk_add_f32 v[28:29], v[30:31], v[28:29]
	v_lshlrev_b32_e32 v31, 16, v17
	v_and_b32_e32 v17, 0xffff0000, v17
	v_lshlrev_b32_e32 v30, 16, v21
	v_pk_mul_f32 v[16:17], v[16:17], v[16:17]
	v_lshlrev_b32_e32 v21, 16, v18
	v_pk_fma_f32 v[16:17], v[30:31], v[30:31], v[16:17]
	v_lshlrev_b32_e32 v27, 16, v1
	v_pk_add_f32 v[16:17], v[16:17], v[28:29]
	v_and_b32_e32 v29, 0xffff0000, v18
	v_and_b32_e32 v28, 0xffff0000, v22
	v_pk_mul_f32 v[28:29], v[28:29], v[28:29]
	v_and_b32_e32 v18, 0xffff0000, v23
	v_pk_fma_f32 v[20:21], v[20:21], v[20:21], v[28:29]
	v_and_b32_e32 v1, 0xffff0000, v1
	v_pk_add_f32 v[16:17], v[20:21], v[16:17]
	v_lshlrev_b32_e32 v21, 16, v19
	v_and_b32_e32 v19, 0xffff0000, v19
	v_lshlrev_b32_e32 v20, 16, v23
	v_pk_mul_f32 v[18:19], v[18:19], v[18:19]
	s_nop 0
	v_pk_fma_f32 v[18:19], v[20:21], v[20:21], v[18:19]
	v_and_b32_e32 v21, 0xffff0000, v8
	v_and_b32_e32 v20, 0xffff0000, v12
	v_pk_add_f32 v[16:17], v[18:19], v[16:17]
	v_lshlrev_b32_e32 v19, 16, v8
	v_lshlrev_b32_e32 v18, 16, v12
	v_pk_mul_f32 v[20:21], v[20:21], v[20:21]
	v_and_b32_e32 v8, 0xffff0000, v13
	v_pk_fma_f32 v[18:19], v[18:19], v[18:19], v[20:21]
	v_lshlrev_b32_e32 v12, 16, v14
	v_pk_add_f32 v[16:17], v[18:19], v[16:17]
	v_lshlrev_b32_e32 v19, 16, v9
	v_and_b32_e32 v9, 0xffff0000, v9
	v_lshlrev_b32_e32 v18, 16, v13
	v_pk_mul_f32 v[8:9], v[8:9], v[8:9]
	v_lshlrev_b32_e32 v13, 16, v10
	v_pk_fma_f32 v[8:9], v[18:19], v[18:19], v[8:9]
	v_and_b32_e32 v19, 0xffff0000, v0
	v_pk_add_f32 v[8:9], v[8:9], v[16:17]
	v_and_b32_e32 v17, 0xffff0000, v10
	v_and_b32_e32 v16, 0xffff0000, v14
	v_pk_mul_f32 v[16:17], v[16:17], v[16:17]
	v_and_b32_e32 v10, 0xffff0000, v15
	v_pk_fma_f32 v[12:13], v[12:13], v[12:13], v[16:17]
	v_lshlrev_b32_e32 v17, 16, v11
	v_and_b32_e32 v11, 0xffff0000, v11
	v_lshlrev_b32_e32 v16, 16, v15
	v_pk_mul_f32 v[10:11], v[10:11], v[10:11]
	v_lshlrev_b32_e32 v15, 16, v0
	v_lshlrev_b32_e32 v14, 16, v4
	v_and_b32_e32 v18, 0xffff0000, v4
	v_and_b32_e32 v0, 0xffff0000, v5
	v_pk_add_f32 v[4:5], v[12:13], v[8:9]
	v_pk_fma_f32 v[8:9], v[16:17], v[16:17], v[10:11]
	v_and_b32_e32 v13, 0xffff0000, v2
	v_pk_add_f32 v[4:5], v[8:9], v[4:5]
	v_pk_mul_f32 v[8:9], v[18:19], v[18:19]
	v_and_b32_e32 v12, 0xffff0000, v6
	v_pk_fma_f32 v[8:9], v[14:15], v[14:15], v[8:9]
	v_pk_mul_f32 v[0:1], v[0:1], v[0:1]
	v_lshlrev_b32_e32 v11, 16, v2
	v_lshlrev_b32_e32 v10, 16, v6
	v_pk_mul_f32 v[12:13], v[12:13], v[12:13]
	v_pk_fma_f32 v[0:1], v[26:27], v[26:27], v[0:1]
	v_pk_fma_f32 v[10:11], v[10:11], v[10:11], v[12:13]
	v_lshlrev_b32_e32 v13, 16, v3
	v_and_b32_e32 v3, 0xffff0000, v3
	v_and_b32_e32 v2, 0xffff0000, v7
	v_pk_add_f32 v[4:5], v[8:9], v[4:5]
	v_lshlrev_b32_e32 v12, 16, v7
	v_pk_mul_f32 v[2:3], v[2:3], v[2:3]
	v_pk_add_f32 v[0:1], v[0:1], v[4:5]
	v_pk_fma_f32 v[2:3], v[12:13], v[12:13], v[2:3]
	v_pk_add_f32 v[0:1], v[10:11], v[0:1]
	s_nop 0
	v_pk_add_f32 v[0:1], v[2:3], v[0:1]
	ds_bpermute_b32 v3, v41, v1
	ds_bpermute_b32 v2, v41, v0
	s_waitcnt lgkmcnt(0)
	v_pk_add_f32 v[0:1], v[0:1], v[2:3]
	ds_bpermute_b32 v3, v42, v1
	ds_bpermute_b32 v2, v42, v0
	s_waitcnt lgkmcnt(0)
	v_pk_add_f32 v[0:1], v[0:1], v[2:3]
	ds_bpermute_b32 v3, v43, v1
	ds_bpermute_b32 v2, v43, v0
	s_and_saveexec_b64 s[2:3], s[40:41]
	s_cbranch_execz .LBB0_307
	s_mov_b32 s42, 0x3b800000
	s_waitcnt lgkmcnt(0)
	v_pk_add_f32 v[0:1], v[0:1], v[2:3]
	s_mov_b32 s43, 0x3b2aaaab
	v_pk_fma_f32 v[0:1], v[0:1], s[42:43], v[188:189] op_sel_hi:[1,1,0]
	v_lshlrev_b64 v[4:5], 2, v[38:39]
	v_mul_f32_e32 v2, 0x4b800000, v1
	v_cmp_gt_f32_e32 vcc, s73, v1
	v_cmp_gt_f32_e64 s[42:43], s73, v0
	v_lshl_add_u64 v[6:7], s[56:57], 0, v[4:5]
	v_cndmask_b32_e32 v1, v1, v2, vcc
	v_rsq_f32_e32 v1, v1
	v_mul_f32_e32 v2, 0x4b800000, v0
	v_cndmask_b32_e64 v0, v0, v2, s[42:43]
	v_rsq_f32_e32 v0, v0
	v_mul_f32_e32 v2, 0x45800000, v1
	v_cndmask_b32_e32 v1, v1, v2, vcc
	global_store_dword v[6:7], v1, off sc1
	v_mul_f32_e32 v1, 0x45800000, v0
	v_cndmask_b32_e64 v2, v0, v1, s[42:43]
	v_lshl_add_u64 v[0:1], s[76:77], 0, v[4:5]
	global_store_dword v[0:1], v2, off sc1
.LBB0_307:
	s_or_b64 exec, exec, s[2:3]
	v_lshlrev_b64 v[8:9], 6, v[38:39]
	s_waitcnt lgkmcnt(0)
	global_load_dwordx4 v[0:3], v[24:25], off offset:2352
	global_load_dwordx4 v[4:7], v[24:25], off offset:2320
	global_load_dwordx4 v[16:19], v[24:25], off offset:2336
	global_load_dwordx4 v[20:23], v[24:25], off offset:2304
	v_lshl_add_u64 v[12:13], s[80:81], 0, v[8:9]
	v_lshl_add_u64 v[98:99], s[82:83], 0, v[8:9]
	global_load_dwordx4 v[8:11], v[12:13], off offset:48
	global_load_dwordx4 v[24:27], v[12:13], off offset:32
	global_load_dwordx4 v[86:89], v[12:13], off offset:16
	global_load_dwordx4 v[90:93], v[12:13], off
	s_nop 0
	global_load_dwordx4 v[12:15], v[98:99], off offset:48
	global_load_dwordx4 v[28:31], v[98:99], off offset:32
	global_load_dwordx4 v[94:97], v[98:99], off offset:16
	s_nop 0
	global_load_dwordx4 v[98:101], v[98:99], off
	s_waitcnt vmcnt(9)
	v_lshlrev_b32_e32 v104, 16, v16
	s_waitcnt vmcnt(8)
	v_lshlrev_b32_e32 v102, 16, v20
	v_and_b32_e32 v103, 0xffff0000, v20
	v_and_b32_e32 v105, 0xffff0000, v16
	s_waitcnt vmcnt(0)
	v_pk_mul_f32 v[106:107], v[98:99], v[104:105]
	v_pk_mul_f32 v[98:99], v[98:99], v[102:103]
	v_pk_fma_f32 v[106:107], v[90:91], v[102:103], v[106:107] neg_lo:[0,0,1] neg_hi:[0,0,1]
	v_pk_fma_f32 v[90:91], v[90:91], v[104:105], v[98:99]
	v_lshlrev_b32_e32 v98, 16, v17
	v_and_b32_e32 v99, 0xffff0000, v17
	v_cvt_pk_bf16_f32 v20, v90, v91
	v_lshlrev_b32_e32 v90, 16, v21
	v_and_b32_e32 v91, 0xffff0000, v21
	v_pk_mul_f32 v[102:103], v[100:101], v[98:99]
	v_cvt_pk_bf16_f32 v16, v106, v107
	v_pk_fma_f32 v[102:103], v[92:93], v[90:91], v[102:103] neg_lo:[0,0,1] neg_hi:[0,0,1]
	v_pk_mul_f32 v[90:91], v[100:101], v[90:91]
	v_cvt_pk_bf16_f32 v17, v102, v103
	v_pk_fma_f32 v[90:91], v[92:93], v[98:99], v[90:91]
	v_lshlrev_b32_e32 v92, 16, v18
	v_and_b32_e32 v93, 0xffff0000, v18
	v_cvt_pk_bf16_f32 v21, v90, v91
	v_lshlrev_b32_e32 v90, 16, v22
	v_and_b32_e32 v91, 0xffff0000, v22
	v_pk_mul_f32 v[98:99], v[94:95], v[92:93]
	s_nop 0
	v_pk_fma_f32 v[98:99], v[86:87], v[90:91], v[98:99] neg_lo:[0,0,1] neg_hi:[0,0,1]
	v_pk_mul_f32 v[90:91], v[94:95], v[90:91]
	v_cvt_pk_bf16_f32 v18, v98, v99
	v_pk_fma_f32 v[86:87], v[86:87], v[92:93], v[90:91]
	v_lshlrev_b32_e32 v90, 16, v19
	v_and_b32_e32 v91, 0xffff0000, v19
	v_cvt_pk_bf16_f32 v22, v86, v87
	v_lshlrev_b32_e32 v86, 16, v23
	v_and_b32_e32 v87, 0xffff0000, v23
	v_pk_mul_f32 v[92:93], v[96:97], v[90:91]
	s_nop 0
	v_pk_fma_f32 v[92:93], v[88:89], v[86:87], v[92:93] neg_lo:[0,0,1] neg_hi:[0,0,1]
	v_pk_mul_f32 v[86:87], v[96:97], v[86:87]
	v_cvt_pk_bf16_f32 v19, v92, v93
	v_pk_fma_f32 v[86:87], v[88:89], v[90:91], v[86:87]
	v_lshlrev_b32_e32 v88, 16, v0
	v_cvt_pk_bf16_f32 v23, v86, v87
	v_lshlrev_b32_e32 v86, 16, v4
	v_and_b32_e32 v87, 0xffff0000, v4
	v_and_b32_e32 v89, 0xffff0000, v0
	v_pk_mul_f32 v[90:91], v[28:29], v[88:89]
	v_pk_mul_f32 v[28:29], v[28:29], v[86:87]
	v_pk_fma_f32 v[90:91], v[24:25], v[86:87], v[90:91] neg_lo:[0,0,1] neg_hi:[0,0,1]
	v_pk_fma_f32 v[24:25], v[24:25], v[88:89], v[28:29]
	v_lshlrev_b32_e32 v28, 16, v1
	v_and_b32_e32 v29, 0xffff0000, v1
	v_cvt_pk_bf16_f32 v4, v24, v25
	v_lshlrev_b32_e32 v24, 16, v5
	v_and_b32_e32 v25, 0xffff0000, v5
	v_pk_mul_f32 v[86:87], v[30:31], v[28:29]
	v_cvt_pk_bf16_f32 v0, v90, v91
	v_pk_fma_f32 v[86:87], v[26:27], v[24:25], v[86:87] neg_lo:[0,0,1] neg_hi:[0,0,1]
	v_pk_mul_f32 v[24:25], v[30:31], v[24:25]
	v_cvt_pk_bf16_f32 v1, v86, v87
	v_pk_fma_f32 v[24:25], v[26:27], v[28:29], v[24:25]
	v_lshlrev_b32_e32 v26, 16, v2
	v_cvt_pk_bf16_f32 v5, v24, v25
	v_lshlrev_b32_e32 v24, 16, v6
	v_and_b32_e32 v25, 0xffff0000, v6
	v_and_b32_e32 v27, 0xffff0000, v2
	v_pk_mul_f32 v[28:29], v[12:13], v[26:27]
	v_pk_mul_f32 v[12:13], v[12:13], v[24:25]
	v_pk_fma_f32 v[28:29], v[8:9], v[24:25], v[28:29] neg_lo:[0,0,1] neg_hi:[0,0,1]
	v_pk_fma_f32 v[8:9], v[8:9], v[26:27], v[12:13]
	v_lshlrev_b32_e32 v12, 16, v3
	v_and_b32_e32 v13, 0xffff0000, v3
	v_cvt_pk_bf16_f32 v6, v8, v9
	v_lshlrev_b32_e32 v8, 16, v7
	v_and_b32_e32 v9, 0xffff0000, v7
	v_pk_mul_f32 v[24:25], v[14:15], v[12:13]
	v_cvt_pk_bf16_f32 v2, v28, v29
	v_pk_fma_f32 v[24:25], v[10:11], v[8:9], v[24:25] neg_lo:[0,0,1] neg_hi:[0,0,1]
	v_pk_mul_f32 v[8:9], v[14:15], v[8:9]
	v_cvt_pk_bf16_f32 v3, v24, v25
	v_pk_fma_f32 v[8:9], v[10:11], v[12:13], v[8:9]
	s_nop 0
	v_cvt_pk_bf16_f32 v7, v8, v9
	v_mad_i64_i32 v[8:9], s[2:3], v38, s33, v[34:35]
	s_mov_b32 s2, 0xd200000
	s_nop 0
	v_add_co_u32_e32 v8, vcc, s2, v8
	s_mov_b64 s[2:3], 0
	s_nop 0
	v_addc_co_u32_e32 v9, vcc, 0, v9, vcc
	global_store_dwordx4 v[8:9], v[16:19], off offset:128 sc1
	global_store_dwordx4 v[8:9], v[0:3], off offset:144 sc1
	global_store_dwordx4 v[8:9], v[20:23], off offset:160 sc1
	global_store_dwordx4 v[8:9], v[4:7], off offset:176 sc1
	v_mov_b32_e32 v2, 0
	v_mov_b32_e32 v0, v57
	v_mov_b32_e32 v1, v45
	v_mov_b32_e32 v3, v2
	v_mov_b32_e32 v8, v2
	v_mov_b32_e32 v9, v2
	v_mov_b32_e32 v6, v2
	v_mov_b32_e32 v7, v2
	v_mov_b32_e32 v4, v2
	v_mov_b32_e32 v5, v2
	s_barrier
.LBB0_308:
	ds_read_b128 v[10:13], v0
	v_add_u32_e32 v1, -1, v1
	v_cmp_eq_u32_e32 vcc, 0, v1
	v_add_u32_e32 v0, 0xfffffc00, v0
	s_or_b64 s[2:3], vcc, s[2:3]
	s_waitcnt lgkmcnt(0)
	v_lshlrev_b32_e32 v14, 16, v10
	v_and_b32_e32 v15, 0xffff0000, v10
	v_lshlrev_b32_e32 v10, 16, v11
	v_and_b32_e32 v11, 0xffff0000, v11
	v_pk_add_f32 v[6:7], v[6:7], v[10:11]
	v_lshlrev_b32_e32 v10, 16, v12
	v_and_b32_e32 v11, 0xffff0000, v12
	v_pk_add_f32 v[4:5], v[4:5], v[10:11]
	v_lshlrev_b32_e32 v10, 16, v13
	v_and_b32_e32 v11, 0xffff0000, v13
	v_pk_add_f32 v[8:9], v[8:9], v[14:15]
	v_pk_add_f32 v[2:3], v[2:3], v[10:11]
	s_andn2_b64 exec, exec, s[2:3]
	s_cbranch_execnz .LBB0_308
	s_or_b64 exec, exec, s[2:3]
	v_add_u32_e32 v10, s10, v46
	v_min_i32_e32 v0, v10, v45
	v_cvt_f32_i32_e32 v1, v0
	ds_read_b128 v[12:15], v70
	ds_read_b128 v[16:19], v71
	v_add_u32_e32 v0, s7, v44
	s_add_i32 s7, s7, s6
	v_div_scale_f32 v11, s[2:3], v1, v1, 1.0
	v_rcp_f32_e32 v20, v11
	v_div_scale_f32 v21, vcc, 1.0, v1, 1.0
	s_waitcnt lgkmcnt(0)
	v_lshlrev_b32_e32 v24, 16, v16
	v_fma_f32 v22, -v11, v20, 1.0
	v_fmac_f32_e32 v20, v22, v20
	v_mul_f32_e32 v22, v21, v20
	v_fma_f32 v23, -v11, v22, v21
	v_fmac_f32_e32 v22, v23, v20
	v_fma_f32 v11, -v11, v22, v21
	v_div_fmas_f32 v11, v11, v20, v22
	v_lshlrev_b32_e32 v22, 16, v12
	v_and_b32_e32 v23, 0xffff0000, v12
	v_and_b32_e32 v25, 0xffff0000, v16
	v_pk_add_f32 v[24:25], v[22:23], v[24:25] neg_lo:[0,1] neg_hi:[0,1]
	v_div_fixup_f32 v20, v11, v1, 1.0
	v_pk_add_f32 v[24:25], v[8:9], v[24:25]
	v_lshlrev_b32_e32 v16, 16, v17
	v_pk_fma_f32 v[8:9], v[20:21], v[24:25], v[22:23] op_sel_hi:[0,1,1] neg_lo:[0,0,1] neg_hi:[0,0,1]
	v_cvt_pk_bf16_f32 v12, v8, v9
	v_lshlrev_b32_e32 v8, 16, v13
	v_and_b32_e32 v9, 0xffff0000, v13
	v_and_b32_e32 v17, 0xffff0000, v17
	v_pk_add_f32 v[16:17], v[8:9], v[16:17] neg_lo:[0,1] neg_hi:[0,1]
	v_ashrrev_i32_e32 v1, 31, v0
	v_pk_add_f32 v[16:17], v[6:7], v[16:17]
	s_cmpk_gt_i32 s7, 0x3fff
	v_pk_fma_f32 v[6:7], v[20:21], v[16:17], v[8:9] op_sel_hi:[0,1,1] neg_lo:[0,0,1] neg_hi:[0,0,1]
	v_cvt_pk_bf16_f32 v13, v6, v7
	v_lshlrev_b32_e32 v6, 16, v14
	v_and_b32_e32 v7, 0xffff0000, v14
	v_lshlrev_b32_e32 v8, 16, v18
	v_and_b32_e32 v9, 0xffff0000, v18
	v_pk_add_f32 v[8:9], v[6:7], v[8:9] neg_lo:[0,1] neg_hi:[0,1]
	s_nop 0
	v_pk_add_f32 v[22:23], v[4:5], v[8:9]
	s_nop 0
	v_pk_fma_f32 v[4:5], v[20:21], v[22:23], v[6:7] op_sel_hi:[0,1,1] neg_lo:[0,0,1] neg_hi:[0,0,1]
	v_cvt_pk_bf16_f32 v14, v4, v5
	v_lshlrev_b32_e32 v4, 16, v15
	v_and_b32_e32 v5, 0xffff0000, v15
	v_lshlrev_b32_e32 v6, 16, v19
	v_and_b32_e32 v7, 0xffff0000, v19
	v_pk_add_f32 v[6:7], v[4:5], v[6:7] neg_lo:[0,1] neg_hi:[0,1]
	s_nop 0
	v_pk_add_f32 v[18:19], v[2:3], v[6:7]
	s_nop 0
	v_pk_fma_f32 v[2:3], v[20:21], v[18:19], v[4:5] op_sel_hi:[0,1,1] neg_lo:[0,0,1] neg_hi:[0,0,1]
	v_cvt_pk_bf16_f32 v15, v2, v3
	v_add_u32_e32 v2, 1, v10
	v_min_i32_e32 v2, v2, v45
	v_cvt_f32_i32_e32 v11, v2
	v_lshlrev_b64 v[2:3], 10, v[0:1]
	v_lshl_add_u64 v[2:3], v[36:37], 0, v[2:3]
	global_store_dwordx4 v[2:3], v[12:15], off sc1
	v_div_scale_f32 v1, s[2:3], v11, v11, 1.0
	v_rcp_f32_e32 v20, v1
	ds_read_b128 v[2:5], v72
	ds_read_b128 v[6:9], v73
	v_fma_f32 v12, -v1, v20, 1.0
	v_fmac_f32_e32 v20, v12, v20
	v_div_scale_f32 v12, vcc, 1.0, v11, 1.0
	v_mul_f32_e32 v13, v12, v20
	v_fma_f32 v14, -v1, v13, v12
	v_fmac_f32_e32 v13, v14, v20
	v_fma_f32 v1, -v1, v13, v12
	v_div_fmas_f32 v1, v1, v20, v13
	s_waitcnt lgkmcnt(1)
	v_lshlrev_b32_e32 v14, 16, v2
	v_and_b32_e32 v15, 0xffff0000, v2
	s_waitcnt lgkmcnt(0)
	v_lshlrev_b32_e32 v20, 16, v6
	v_and_b32_e32 v21, 0xffff0000, v6
	v_pk_add_f32 v[20:21], v[14:15], v[20:21] neg_lo:[0,1] neg_hi:[0,1]
	v_div_fixup_f32 v12, v1, v11, 1.0
	v_pk_add_f32 v[20:21], v[24:25], v[20:21]
	v_lshlrev_b32_e32 v6, 16, v7
	v_pk_fma_f32 v[14:15], v[12:13], v[20:21], v[14:15] op_sel_hi:[0,1,1] neg_lo:[0,0,1] neg_hi:[0,0,1]
	v_cvt_pk_bf16_f32 v2, v14, v15
	v_lshlrev_b32_e32 v14, 16, v3
	v_and_b32_e32 v15, 0xffff0000, v3
	v_and_b32_e32 v7, 0xffff0000, v7
	v_pk_add_f32 v[6:7], v[14:15], v[6:7] neg_lo:[0,1] neg_hi:[0,1]
	v_or_b32_e32 v1, 2, v10
	v_pk_add_f32 v[16:17], v[16:17], v[6:7]
	v_min_i32_e32 v1, v1, v45
	v_pk_fma_f32 v[6:7], v[12:13], v[16:17], v[14:15] op_sel_hi:[0,1,1] neg_lo:[0,0,1] neg_hi:[0,0,1]
	v_cvt_pk_bf16_f32 v3, v6, v7
	v_lshlrev_b32_e32 v6, 16, v4
	v_and_b32_e32 v7, 0xffff0000, v4
	v_lshlrev_b32_e32 v14, 16, v8
	v_and_b32_e32 v15, 0xffff0000, v8
	v_pk_add_f32 v[14:15], v[6:7], v[14:15] neg_lo:[0,1] neg_hi:[0,1]
	v_cvt_f32_i32_e32 v1, v1
	v_pk_add_f32 v[14:15], v[22:23], v[14:15]
	v_lshlrev_b32_e32 v8, 16, v9
	v_pk_fma_f32 v[6:7], v[12:13], v[14:15], v[6:7] op_sel_hi:[0,1,1] neg_lo:[0,0,1] neg_hi:[0,0,1]
	v_cvt_pk_bf16_f32 v4, v6, v7
	v_lshlrev_b32_e32 v6, 16, v5
	v_and_b32_e32 v7, 0xffff0000, v5
	v_and_b32_e32 v9, 0xffff0000, v9
	v_pk_add_f32 v[8:9], v[6:7], v[8:9] neg_lo:[0,1] neg_hi:[0,1]
	v_div_scale_f32 v11, s[2:3], v1, v1, 1.0
	v_pk_add_f32 v[18:19], v[18:19], v[8:9]
	s_nop 0
	v_pk_fma_f32 v[6:7], v[12:13], v[18:19], v[6:7] op_sel_hi:[0,1,1] neg_lo:[0,0,1] neg_hi:[0,0,1]
	v_cvt_pk_bf16_f32 v5, v6, v7
	v_or_b32_e32 v6, 1, v0
	v_rcp_f32_e32 v12, v11
	v_ashrrev_i32_e32 v7, 31, v6
	v_lshlrev_b64 v[6:7], 10, v[6:7]
	v_lshl_add_u64 v[6:7], v[36:37], 0, v[6:7]
	global_store_dwordx4 v[6:7], v[2:5], off sc1
	v_fma_f32 v13, -v11, v12, 1.0
	ds_read_b128 v[2:5], v74
	ds_read_b128 v[6:9], v75
	v_fmac_f32_e32 v12, v13, v12
	v_div_scale_f32 v13, vcc, 1.0, v1, 1.0
	v_mul_f32_e32 v22, v13, v12
	v_fma_f32 v23, -v11, v22, v13
	v_fmac_f32_e32 v22, v23, v12
	v_fma_f32 v11, -v11, v22, v13
	v_div_fmas_f32 v11, v11, v12, v22
	s_waitcnt lgkmcnt(1)
	v_lshlrev_b32_e32 v22, 16, v2
	v_and_b32_e32 v23, 0xffff0000, v2
	s_waitcnt lgkmcnt(0)
	v_lshlrev_b32_e32 v24, 16, v6
	v_and_b32_e32 v25, 0xffff0000, v6
	v_pk_add_f32 v[24:25], v[22:23], v[24:25] neg_lo:[0,1] neg_hi:[0,1]
	v_div_fixup_f32 v12, v11, v1, 1.0
	v_pk_add_f32 v[20:21], v[20:21], v[24:25]
	v_lshlrev_b32_e32 v6, 16, v7
	v_pk_fma_f32 v[22:23], v[12:13], v[20:21], v[22:23] op_sel_hi:[0,1,1] neg_lo:[0,0,1] neg_hi:[0,0,1]
	v_cvt_pk_bf16_f32 v2, v22, v23
	v_lshlrev_b32_e32 v22, 16, v3
	v_and_b32_e32 v23, 0xffff0000, v3
	v_and_b32_e32 v7, 0xffff0000, v7
	v_pk_add_f32 v[6:7], v[22:23], v[6:7] neg_lo:[0,1] neg_hi:[0,1]
	v_add_u32_e32 v1, 3, v10
	v_pk_add_f32 v[16:17], v[16:17], v[6:7]
	v_min_i32_e32 v1, v1, v45
	v_pk_fma_f32 v[6:7], v[12:13], v[16:17], v[22:23] op_sel_hi:[0,1,1] neg_lo:[0,0,1] neg_hi:[0,0,1]
	v_cvt_pk_bf16_f32 v3, v6, v7
	v_lshlrev_b32_e32 v6, 16, v4
	v_and_b32_e32 v7, 0xffff0000, v4
	v_lshlrev_b32_e32 v22, 16, v8
	v_and_b32_e32 v23, 0xffff0000, v8
	v_pk_add_f32 v[22:23], v[6:7], v[22:23] neg_lo:[0,1] neg_hi:[0,1]
	v_cvt_f32_i32_e32 v1, v1
	v_pk_add_f32 v[14:15], v[14:15], v[22:23]
	v_lshlrev_b32_e32 v8, 16, v9
	v_pk_fma_f32 v[6:7], v[12:13], v[14:15], v[6:7] op_sel_hi:[0,1,1] neg_lo:[0,0,1] neg_hi:[0,0,1]
	v_cvt_pk_bf16_f32 v4, v6, v7
	v_lshlrev_b32_e32 v6, 16, v5
	v_and_b32_e32 v7, 0xffff0000, v5
	v_and_b32_e32 v9, 0xffff0000, v9
	v_pk_add_f32 v[8:9], v[6:7], v[8:9] neg_lo:[0,1] neg_hi:[0,1]
	v_div_scale_f32 v11, s[2:3], v1, v1, 1.0
	v_pk_add_f32 v[18:19], v[18:19], v[8:9]
	s_nop 0
	v_pk_fma_f32 v[6:7], v[12:13], v[18:19], v[6:7] op_sel_hi:[0,1,1] neg_lo:[0,0,1] neg_hi:[0,0,1]
	v_cvt_pk_bf16_f32 v5, v6, v7
	v_or_b32_e32 v6, 2, v0
	v_rcp_f32_e32 v12, v11
	v_ashrrev_i32_e32 v7, 31, v6
	v_lshlrev_b64 v[6:7], 10, v[6:7]
	v_lshl_add_u64 v[6:7], v[36:37], 0, v[6:7]
	global_store_dwordx4 v[6:7], v[2:5], off sc1
	v_fma_f32 v13, -v11, v12, 1.0
	ds_read_b128 v[2:5], v76
	ds_read_b128 v[6:9], v77
	v_fmac_f32_e32 v12, v13, v12
	v_div_scale_f32 v13, vcc, 1.0, v1, 1.0
	v_mul_f32_e32 v22, v13, v12
	v_fma_f32 v23, -v11, v22, v13
	v_fmac_f32_e32 v22, v23, v12
	v_fma_f32 v11, -v11, v22, v13
	v_div_fmas_f32 v11, v11, v12, v22
	s_waitcnt lgkmcnt(1)
	v_lshlrev_b32_e32 v22, 16, v2
	v_and_b32_e32 v23, 0xffff0000, v2
	s_waitcnt lgkmcnt(0)
	v_lshlrev_b32_e32 v24, 16, v6
	v_and_b32_e32 v25, 0xffff0000, v6
	v_pk_add_f32 v[24:25], v[22:23], v[24:25] neg_lo:[0,1] neg_hi:[0,1]
	v_div_fixup_f32 v12, v11, v1, 1.0
	v_pk_add_f32 v[20:21], v[20:21], v[24:25]
	v_lshlrev_b32_e32 v6, 16, v7
	v_pk_fma_f32 v[22:23], v[12:13], v[20:21], v[22:23] op_sel_hi:[0,1,1] neg_lo:[0,0,1] neg_hi:[0,0,1]
	v_cvt_pk_bf16_f32 v2, v22, v23
	v_lshlrev_b32_e32 v22, 16, v3
	v_and_b32_e32 v23, 0xffff0000, v3
	v_and_b32_e32 v7, 0xffff0000, v7
	v_pk_add_f32 v[6:7], v[22:23], v[6:7] neg_lo:[0,1] neg_hi:[0,1]
	v_or_b32_e32 v1, 4, v10
	v_pk_add_f32 v[16:17], v[16:17], v[6:7]
	v_min_i32_e32 v1, v1, v45
	v_pk_fma_f32 v[6:7], v[12:13], v[16:17], v[22:23] op_sel_hi:[0,1,1] neg_lo:[0,0,1] neg_hi:[0,0,1]
	v_cvt_pk_bf16_f32 v3, v6, v7
	v_lshlrev_b32_e32 v6, 16, v4
	v_and_b32_e32 v7, 0xffff0000, v4
	v_lshlrev_b32_e32 v22, 16, v8
	v_and_b32_e32 v23, 0xffff0000, v8
	v_pk_add_f32 v[22:23], v[6:7], v[22:23] neg_lo:[0,1] neg_hi:[0,1]
	v_cvt_f32_i32_e32 v1, v1
	v_pk_add_f32 v[14:15], v[14:15], v[22:23]
	v_lshlrev_b32_e32 v8, 16, v9
	v_pk_fma_f32 v[6:7], v[12:13], v[14:15], v[6:7] op_sel_hi:[0,1,1] neg_lo:[0,0,1] neg_hi:[0,0,1]
	v_cvt_pk_bf16_f32 v4, v6, v7
	v_lshlrev_b32_e32 v6, 16, v5
	v_and_b32_e32 v7, 0xffff0000, v5
	v_and_b32_e32 v9, 0xffff0000, v9
	v_pk_add_f32 v[8:9], v[6:7], v[8:9] neg_lo:[0,1] neg_hi:[0,1]
	v_div_scale_f32 v11, s[2:3], v1, v1, 1.0
	v_pk_add_f32 v[18:19], v[18:19], v[8:9]
	s_nop 0
	v_pk_fma_f32 v[6:7], v[12:13], v[18:19], v[6:7] op_sel_hi:[0,1,1] neg_lo:[0,0,1] neg_hi:[0,0,1]
	v_cvt_pk_bf16_f32 v5, v6, v7
	v_or_b32_e32 v6, 3, v0
	v_rcp_f32_e32 v12, v11
	v_ashrrev_i32_e32 v7, 31, v6
	v_lshlrev_b64 v[6:7], 10, v[6:7]
	v_lshl_add_u64 v[6:7], v[36:37], 0, v[6:7]
	global_store_dwordx4 v[6:7], v[2:5], off sc1
	v_fma_f32 v13, -v11, v12, 1.0
	ds_read_b128 v[2:5], v78
	ds_read_b128 v[6:9], v79
	v_fmac_f32_e32 v12, v13, v12
	v_div_scale_f32 v13, vcc, 1.0, v1, 1.0
	v_mul_f32_e32 v22, v13, v12
	v_fma_f32 v23, -v11, v22, v13
	v_fmac_f32_e32 v22, v23, v12
	v_fma_f32 v11, -v11, v22, v13
	v_div_fmas_f32 v11, v11, v12, v22
	s_waitcnt lgkmcnt(1)
	v_lshlrev_b32_e32 v22, 16, v2
	v_and_b32_e32 v23, 0xffff0000, v2
	s_waitcnt lgkmcnt(0)
	v_lshlrev_b32_e32 v24, 16, v6
	v_and_b32_e32 v25, 0xffff0000, v6
	v_pk_add_f32 v[24:25], v[22:23], v[24:25] neg_lo:[0,1] neg_hi:[0,1]
	v_div_fixup_f32 v12, v11, v1, 1.0
	v_pk_add_f32 v[20:21], v[20:21], v[24:25]
	v_lshlrev_b32_e32 v6, 16, v7
	v_pk_fma_f32 v[22:23], v[12:13], v[20:21], v[22:23] op_sel_hi:[0,1,1] neg_lo:[0,0,1] neg_hi:[0,0,1]
	v_cvt_pk_bf16_f32 v2, v22, v23
	v_lshlrev_b32_e32 v22, 16, v3
	v_and_b32_e32 v23, 0xffff0000, v3
	v_and_b32_e32 v7, 0xffff0000, v7
	v_pk_add_f32 v[6:7], v[22:23], v[6:7] neg_lo:[0,1] neg_hi:[0,1]
	v_add_u32_e32 v1, 5, v10
	v_pk_add_f32 v[16:17], v[16:17], v[6:7]
	v_min_i32_e32 v1, v1, v45
	v_pk_fma_f32 v[6:7], v[12:13], v[16:17], v[22:23] op_sel_hi:[0,1,1] neg_lo:[0,0,1] neg_hi:[0,0,1]
	v_cvt_pk_bf16_f32 v3, v6, v7
	v_lshlrev_b32_e32 v6, 16, v4
	v_and_b32_e32 v7, 0xffff0000, v4
	v_lshlrev_b32_e32 v22, 16, v8
	v_and_b32_e32 v23, 0xffff0000, v8
	v_pk_add_f32 v[22:23], v[6:7], v[22:23] neg_lo:[0,1] neg_hi:[0,1]
	v_cvt_f32_i32_e32 v1, v1
	v_pk_add_f32 v[14:15], v[14:15], v[22:23]
	v_lshlrev_b32_e32 v8, 16, v9
	v_pk_fma_f32 v[6:7], v[12:13], v[14:15], v[6:7] op_sel_hi:[0,1,1] neg_lo:[0,0,1] neg_hi:[0,0,1]
	v_cvt_pk_bf16_f32 v4, v6, v7
	v_lshlrev_b32_e32 v6, 16, v5
	v_and_b32_e32 v7, 0xffff0000, v5
	v_and_b32_e32 v9, 0xffff0000, v9
	v_pk_add_f32 v[8:9], v[6:7], v[8:9] neg_lo:[0,1] neg_hi:[0,1]
	v_div_scale_f32 v11, s[2:3], v1, v1, 1.0
	v_pk_add_f32 v[18:19], v[18:19], v[8:9]
	s_nop 0
	v_pk_fma_f32 v[6:7], v[12:13], v[18:19], v[6:7] op_sel_hi:[0,1,1] neg_lo:[0,0,1] neg_hi:[0,0,1]
	v_cvt_pk_bf16_f32 v5, v6, v7
	v_or_b32_e32 v6, 4, v0
	v_rcp_f32_e32 v12, v11
	v_ashrrev_i32_e32 v7, 31, v6
	v_lshlrev_b64 v[6:7], 10, v[6:7]
	v_lshl_add_u64 v[6:7], v[36:37], 0, v[6:7]
	global_store_dwordx4 v[6:7], v[2:5], off sc1
	v_fma_f32 v13, -v11, v12, 1.0
	ds_read_b128 v[2:5], v80
	ds_read_b128 v[6:9], v81
	v_fmac_f32_e32 v12, v13, v12
	v_div_scale_f32 v13, vcc, 1.0, v1, 1.0
	v_mul_f32_e32 v22, v13, v12
	v_fma_f32 v23, -v11, v22, v13
	v_fmac_f32_e32 v22, v23, v12
	v_fma_f32 v11, -v11, v22, v13
	v_div_fmas_f32 v11, v11, v12, v22
	s_waitcnt lgkmcnt(1)
	v_lshlrev_b32_e32 v22, 16, v2
	v_and_b32_e32 v23, 0xffff0000, v2
	s_waitcnt lgkmcnt(0)
	v_lshlrev_b32_e32 v24, 16, v6
	v_and_b32_e32 v25, 0xffff0000, v6
	v_pk_add_f32 v[24:25], v[22:23], v[24:25] neg_lo:[0,1] neg_hi:[0,1]
	v_div_fixup_f32 v12, v11, v1, 1.0
	v_pk_add_f32 v[20:21], v[20:21], v[24:25]
	v_lshlrev_b32_e32 v6, 16, v7
	v_pk_fma_f32 v[22:23], v[12:13], v[20:21], v[22:23] op_sel_hi:[0,1,1] neg_lo:[0,0,1] neg_hi:[0,0,1]
	v_cvt_pk_bf16_f32 v2, v22, v23
	v_lshlrev_b32_e32 v22, 16, v3
	v_and_b32_e32 v23, 0xffff0000, v3
	v_and_b32_e32 v7, 0xffff0000, v7
	v_pk_add_f32 v[6:7], v[22:23], v[6:7] neg_lo:[0,1] neg_hi:[0,1]
	v_or_b32_e32 v1, 6, v10
	v_pk_add_f32 v[16:17], v[16:17], v[6:7]
	v_min_i32_e32 v1, v1, v45
	v_pk_fma_f32 v[6:7], v[12:13], v[16:17], v[22:23] op_sel_hi:[0,1,1] neg_lo:[0,0,1] neg_hi:[0,0,1]
	v_cvt_pk_bf16_f32 v3, v6, v7
	v_lshlrev_b32_e32 v6, 16, v4
	v_and_b32_e32 v7, 0xffff0000, v4
	v_lshlrev_b32_e32 v22, 16, v8
	v_and_b32_e32 v23, 0xffff0000, v8
	v_pk_add_f32 v[22:23], v[6:7], v[22:23] neg_lo:[0,1] neg_hi:[0,1]
	v_cvt_f32_i32_e32 v1, v1
	v_pk_add_f32 v[14:15], v[14:15], v[22:23]
	v_lshlrev_b32_e32 v8, 16, v9
	v_pk_fma_f32 v[6:7], v[12:13], v[14:15], v[6:7] op_sel_hi:[0,1,1] neg_lo:[0,0,1] neg_hi:[0,0,1]
	v_cvt_pk_bf16_f32 v4, v6, v7
	v_lshlrev_b32_e32 v6, 16, v5
	v_and_b32_e32 v7, 0xffff0000, v5
	v_and_b32_e32 v9, 0xffff0000, v9
	v_pk_add_f32 v[8:9], v[6:7], v[8:9] neg_lo:[0,1] neg_hi:[0,1]
	v_div_scale_f32 v11, s[2:3], v1, v1, 1.0
	v_pk_add_f32 v[18:19], v[18:19], v[8:9]
	s_nop 0
	v_pk_fma_f32 v[6:7], v[12:13], v[18:19], v[6:7] op_sel_hi:[0,1,1] neg_lo:[0,0,1] neg_hi:[0,0,1]
	v_cvt_pk_bf16_f32 v5, v6, v7
	v_or_b32_e32 v6, 5, v0
	v_rcp_f32_e32 v12, v11
	v_ashrrev_i32_e32 v7, 31, v6
	v_lshlrev_b64 v[6:7], 10, v[6:7]
	v_lshl_add_u64 v[6:7], v[36:37], 0, v[6:7]
	global_store_dwordx4 v[6:7], v[2:5], off sc1
	v_fma_f32 v13, -v11, v12, 1.0
	ds_read_b128 v[2:5], v82
	ds_read_b128 v[6:9], v83
	v_fmac_f32_e32 v12, v13, v12
	v_div_scale_f32 v13, vcc, 1.0, v1, 1.0
	v_mul_f32_e32 v22, v13, v12
	v_fma_f32 v23, -v11, v22, v13
	v_fmac_f32_e32 v22, v23, v12
	v_fma_f32 v11, -v11, v22, v13
	v_div_fmas_f32 v11, v11, v12, v22
	s_waitcnt lgkmcnt(1)
	v_lshlrev_b32_e32 v22, 16, v2
	v_and_b32_e32 v23, 0xffff0000, v2
	s_waitcnt lgkmcnt(0)
	v_lshlrev_b32_e32 v24, 16, v6
	v_and_b32_e32 v25, 0xffff0000, v6
	v_pk_add_f32 v[24:25], v[22:23], v[24:25] neg_lo:[0,1] neg_hi:[0,1]
	v_div_fixup_f32 v12, v11, v1, 1.0
	v_pk_add_f32 v[20:21], v[20:21], v[24:25]
	v_lshlrev_b32_e32 v6, 16, v7
	v_pk_fma_f32 v[22:23], v[12:13], v[20:21], v[22:23] op_sel_hi:[0,1,1] neg_lo:[0,0,1] neg_hi:[0,0,1]
	v_cvt_pk_bf16_f32 v2, v22, v23
	v_lshlrev_b32_e32 v22, 16, v3
	v_and_b32_e32 v23, 0xffff0000, v3
	v_and_b32_e32 v7, 0xffff0000, v7
	v_pk_add_f32 v[6:7], v[22:23], v[6:7] neg_lo:[0,1] neg_hi:[0,1]
	v_add_u32_e32 v1, 7, v10
	v_pk_add_f32 v[16:17], v[16:17], v[6:7]
	v_min_i32_e32 v1, v1, v45
	v_pk_fma_f32 v[6:7], v[12:13], v[16:17], v[22:23] op_sel_hi:[0,1,1] neg_lo:[0,0,1] neg_hi:[0,0,1]
	v_cvt_pk_bf16_f32 v3, v6, v7
	v_lshlrev_b32_e32 v6, 16, v4
	v_and_b32_e32 v7, 0xffff0000, v4
	v_lshlrev_b32_e32 v22, 16, v8
	v_and_b32_e32 v23, 0xffff0000, v8
	v_pk_add_f32 v[22:23], v[6:7], v[22:23] neg_lo:[0,1] neg_hi:[0,1]
	v_cvt_f32_i32_e32 v1, v1
	v_pk_add_f32 v[14:15], v[14:15], v[22:23]
	v_lshlrev_b32_e32 v8, 16, v9
	v_pk_fma_f32 v[6:7], v[12:13], v[14:15], v[6:7] op_sel_hi:[0,1,1] neg_lo:[0,0,1] neg_hi:[0,0,1]
	v_cvt_pk_bf16_f32 v4, v6, v7
	v_lshlrev_b32_e32 v6, 16, v5
	v_and_b32_e32 v7, 0xffff0000, v5
	v_and_b32_e32 v9, 0xffff0000, v9
	v_pk_add_f32 v[8:9], v[6:7], v[8:9] neg_lo:[0,1] neg_hi:[0,1]
	v_div_scale_f32 v10, s[2:3], v1, v1, 1.0
	v_pk_add_f32 v[18:19], v[18:19], v[8:9]
	v_rcp_f32_e32 v11, v10
	v_pk_fma_f32 v[6:7], v[12:13], v[18:19], v[6:7] op_sel_hi:[0,1,1] neg_lo:[0,0,1] neg_hi:[0,0,1]
	v_cvt_pk_bf16_f32 v5, v6, v7
	v_or_b32_e32 v6, 6, v0
	v_ashrrev_i32_e32 v7, 31, v6
	v_lshlrev_b64 v[6:7], 10, v[6:7]
	v_lshl_add_u64 v[6:7], v[36:37], 0, v[6:7]
	global_store_dwordx4 v[6:7], v[2:5], off sc1
	v_fma_f32 v12, -v10, v11, 1.0
	ds_read_b128 v[2:5], v84
	ds_read_b128 v[6:9], v85
	v_fmac_f32_e32 v11, v12, v11
	v_div_scale_f32 v12, vcc, 1.0, v1, 1.0
	v_mul_f32_e32 v13, v12, v11
	v_fma_f32 v22, -v10, v13, v12
	v_fmac_f32_e32 v13, v22, v11
	v_fma_f32 v10, -v10, v13, v12
	v_div_fmas_f32 v10, v10, v11, v13
	s_waitcnt lgkmcnt(1)
	v_lshlrev_b32_e32 v12, 16, v2
	v_and_b32_e32 v13, 0xffff0000, v2
	s_waitcnt lgkmcnt(0)
	v_lshlrev_b32_e32 v22, 16, v6
	v_and_b32_e32 v23, 0xffff0000, v6
	v_pk_add_f32 v[22:23], v[12:13], v[22:23] neg_lo:[0,1] neg_hi:[0,1]
	v_div_fixup_f32 v10, v10, v1, 1.0
	v_pk_add_f32 v[20:21], v[20:21], v[22:23]
	v_lshlrev_b32_e32 v6, 16, v7
	v_pk_fma_f32 v[12:13], v[10:11], v[20:21], v[12:13] op_sel_hi:[0,1,1] neg_lo:[0,0,1] neg_hi:[0,0,1]
	v_cvt_pk_bf16_f32 v2, v12, v13
	v_lshlrev_b32_e32 v12, 16, v3
	v_and_b32_e32 v13, 0xffff0000, v3
	v_and_b32_e32 v7, 0xffff0000, v7
	v_pk_add_f32 v[6:7], v[12:13], v[6:7] neg_lo:[0,1] neg_hi:[0,1]
	v_or_b32_e32 v0, 7, v0
	v_pk_add_f32 v[6:7], v[16:17], v[6:7]
	v_ashrrev_i32_e32 v1, 31, v0
	v_pk_fma_f32 v[6:7], v[10:11], v[6:7], v[12:13] op_sel_hi:[0,1,1] neg_lo:[0,0,1] neg_hi:[0,0,1]
	v_cvt_pk_bf16_f32 v3, v6, v7
	v_lshlrev_b32_e32 v6, 16, v4
	v_and_b32_e32 v7, 0xffff0000, v4
	v_lshlrev_b32_e32 v12, 16, v8
	v_and_b32_e32 v13, 0xffff0000, v8
	v_pk_add_f32 v[12:13], v[6:7], v[12:13] neg_lo:[0,1] neg_hi:[0,1]
	v_lshlrev_b32_e32 v8, 16, v9
	v_pk_add_f32 v[12:13], v[14:15], v[12:13]
	v_and_b32_e32 v9, 0xffff0000, v9
	v_pk_fma_f32 v[6:7], v[10:11], v[12:13], v[6:7] op_sel_hi:[0,1,1] neg_lo:[0,0,1] neg_hi:[0,0,1]
	v_cvt_pk_bf16_f32 v4, v6, v7
	v_lshlrev_b32_e32 v6, 16, v5
	v_and_b32_e32 v7, 0xffff0000, v5
	v_pk_add_f32 v[8:9], v[6:7], v[8:9] neg_lo:[0,1] neg_hi:[0,1]
	v_lshlrev_b64 v[0:1], 10, v[0:1]
	v_pk_add_f32 v[8:9], v[18:19], v[8:9]
	v_lshl_add_u64 v[0:1], v[36:37], 0, v[0:1]
	v_pk_fma_f32 v[6:7], v[10:11], v[8:9], v[6:7] op_sel_hi:[0,1,1] neg_lo:[0,0,1] neg_hi:[0,0,1]
	v_cvt_pk_bf16_f32 v5, v6, v7
	global_store_dwordx4 v[0:1], v[2:5], off sc1
	s_cbranch_scc0 .LBB0_285
	s_mov_b32 s96, s88
	s_mov_b32 s22, s74
	s_mov_b32 s62, s75
	s_mov_b32 s63, s16
	s_mov_b64 s[0:1], 0

.Lrp_done:
	s_cmp_eq_u32 s14, 11
	s_cbranch_scc1 .LBB0_681
	s_cmp_ge_i32 s17, s15
	s_cbranch_scc1 .LBB0_681
	v_readlane_b32 s99, v255, 59
	s_lshr_b32 s98, 0x1745d0, s14
	s_and_b32 s98, s98, s99
	s_bitcmp1_b32 s98, 0
	s_cbranch_scc0 .Lgg_no
	s_waitcnt vmcnt(0)
	s_barrier
	s_and_saveexec_b64 s[2:3], s[86:87]
	s_cbranch_execz .Lgg_join
	v_readlane_b32 s6, v253, 55
	s_and_b32 s7, s6, 7
	s_lshl_b32 s7, s7, 3
	s_bfe_u32 s6, s6, 0x30003
	s_add_i32 s6, s6, s7
	s_cmp_eq_u32 s14, 4
	s_cselect_b32 s11, 1, 0
	s_cmp_eq_u32 s14, 14
	s_cselect_b32 s11, 1, s11
	s_cmp_eq_u32 s11, 1
	s_cbranch_scc0 .Lgg_notprep
	s_cmp_eq_u32 s14, 14
	s_cselect_b32 s10, 4, 0
	s_add_i32 s10, s10, 0x4068
	v_readlane_b32 s7, v253, 55
	s_lshr_b32 s8, s7, 2
	s_lshl_b32 s8, s8, 8
	s_add_i32 s8, s8, s10
	v_mov_b32_e32 v20, s8
	global_atomic_add v20, v202, s[12:13]
	s_cmp_lt_u32 s7, 192
	s_cbranch_scc0 .Lgg_pb
	s_mul_hi_u32 s8, s7, 0xaaaaaaab
	s_lshr_b32 s8, s8, 1
	s_lshr_b32 s9, s7, 1
	s_add_i32 s9, s9, 32
	s_add_i32 s11, s7, -64
	s_lshr_b32 s11, s11, 1
	s_cmp_lt_u32 s7, 64
	s_cselect_b32 s9, s9, s11
	s_mov_b32 s11, s9
	s_branch .Lgg_pw
.Lgg_pb:
	s_add_i32 s7, s7, 0xffffff40
	s_mul_i32 s7, s7, 3
	s_and_b32 s8, s7, 127
	s_lshr_b32 s8, s8, 1
	s_add_i32 s7, s7, 1
	s_and_b32 s9, s7, 127
	s_lshr_b32 s9, s9, 1
	s_add_i32 s7, s7, 1
	s_and_b32 s11, s7, 127
	s_lshr_b32 s11, s11, 1
.Lgg_pw:
	s_lshl_b32 s8, s8, 8
	s_add_i32 s8, s8, s10
	v_mov_b32_e32 v21, s8
	s_lshl_b32 s9, s9, 8
	s_add_i32 s9, s9, s10
	v_mov_b32_e32 v23, s9
	s_lshl_b32 s11, s11, 8
	s_add_i32 s11, s11, s10
	v_mov_b32_e32 v24, s11
	s_mov_b32 s58, 0
.Lgg_pspin:
	global_load_dword v26, v21, s[12:13] sc1
	global_load_dword v27, v23, s[12:13] sc1
	global_load_dword v28, v24, s[12:13] sc1
	s_waitcnt vmcnt(0)
	v_min3_u32 v26, v26, v27, v28
	v_cmp_gt_u32_e32 vcc, 4, v26
	s_cbranch_vccz .Lgg_done
	s_sleep 1
	s_add_i32 s58, s58, 1
	s_cmp_lt_u32 s58, 0x40001
	s_cbranch_scc1 .Lgg_pspin
	s_branch .Lgg_done
.Lgg_notprep:
	s_cmp_eq_u32 s14, 16
	s_cselect_b32 s10, 4, 0
	s_cmp_eq_u32 s14, 17
	s_cselect_b32 s10, 4, s10
	s_cmp_eq_u32 s14, 6
	s_cselect_b32 s11, 1, 0
	s_cmp_eq_u32 s14, 16
	s_cselect_b32 s11, 1, s11
	s_cmp_eq_u32 s11, 1
	s_cbranch_scc0 .Lgg_std
	v_readlane_b32 s7, v253, 55
	s_bfe_u32 s8, s7, 0x30003
	s_bfe_u32 s7, s7, 0x20001
	s_lshl_b32 s7, s7, 4
	s_add_i32 s7, s7, s8
	s_lshl_b32 s7, s7, 8
	s_add_i32 s7, s7, 0x4058
	s_add_i32 s7, s7, s10
	v_mov_b32_e32 v20, s7
	s_add_i32 s9, s10, 0x4060
	v_mov_b32_e32 v21, s9
	global_atomic_add v20, v202, s[12:13]
	global_atomic_add v21, v202, s[12:13]
	s_lshl_b32 s7, s6, 8
	s_add_i32 s7, s7, 0x4058
	s_add_i32 s7, s7, s10
	v_mov_b32_e32 v20, s7
	s_mov_b32 s58, 0
